# C1: SC-phase weight-conversion loops keep 16 loads in flight (was 2) + E3 saddr DMA
# speedup vs baseline: 1.0147x; 1.0147x over previous
.LBB0_72:
	s_lshl_b32 s29, s11, 1
	s_lshl_b32 s45, s21, 1
	v_or_b32_e32 v21, s29, v3
	v_or_b32_e32 v23, s45, v2
	v_add_lshl_u32 v0, v21, s20, 10
	v_add_lshl_u32 v25, v23, s16, 10
	v_or_b32_e32 v24, v5, v0
	v_or_b32_e32 v0, v22, v25
	v_lshl_add_u64 v[26:27], v[0:1], 2, s[2:3]
	v_mov_b32_e32 v25, v1
	v_lshl_add_u64 v[24:25], v[24:25], 2, s[2:3]
	global_load_dword v40, v[26:27], off
	global_load_dword v41, v[24:25], off
	v_mad_u64_u32 v[56:57], s[46:47], v23, s81, v[6:7]
	v_mad_u64_u32 v[58:59], s[46:47], v21, s81, v[6:7]
	s_add_i32 s46, s29, 4
	s_add_i32 s47, s45, 4
	v_or_b32_e32 v21, s46, v3
	v_or_b32_e32 v23, s47, v2
	v_add_lshl_u32 v25, v23, s16, 10
	s_add_i32 s21, s21, 16
	s_add_i32 s11, s11, 16
	s_add_i32 s28, s28, -16
	v_add_lshl_u32 v0, v21, s20, 10
	v_or_b32_e32 v24, v5, v0
	v_or_b32_e32 v0, v22, v25
	v_lshl_add_u64 v[26:27], v[0:1], 2, s[2:3]
	v_mov_b32_e32 v25, v1
	v_lshl_add_u64 v[24:25], v[24:25], 2, s[2:3]
	global_load_dword v42, v[26:27], off
	global_load_dword v43, v[24:25], off
	v_mad_u64_u32 v[60:61], s[46:47], v23, s81, v[6:7]
	v_mad_u64_u32 v[62:63], s[46:47], v21, s81, v[6:7]
	s_add_i32 s46, s29, 8
	s_add_i32 s47, s45, 8
	v_or_b32_e32 v21, s46, v3
	v_or_b32_e32 v23, s47, v2
	v_add_lshl_u32 v25, v23, s16, 10
	v_add_lshl_u32 v0, v21, s20, 10
	v_or_b32_e32 v24, v5, v0
	v_or_b32_e32 v0, v22, v25
	v_lshl_add_u64 v[26:27], v[0:1], 2, s[2:3]
	v_mov_b32_e32 v25, v1
	v_lshl_add_u64 v[24:25], v[24:25], 2, s[2:3]
	global_load_dword v44, v[26:27], off
	global_load_dword v45, v[24:25], off
	v_mad_u64_u32 v[64:65], s[46:47], v23, s81, v[6:7]
	v_mad_u64_u32 v[66:67], s[46:47], v21, s81, v[6:7]
	s_add_i32 s46, s29, 12
	s_add_i32 s47, s45, 12
	v_or_b32_e32 v21, s46, v3
	v_or_b32_e32 v23, s47, v2
	v_add_lshl_u32 v25, v23, s16, 10
	v_add_lshl_u32 v0, v21, s20, 10
	v_or_b32_e32 v24, v5, v0
	v_or_b32_e32 v0, v22, v25
	v_lshl_add_u64 v[26:27], v[0:1], 2, s[2:3]
	v_mov_b32_e32 v25, v1
	v_lshl_add_u64 v[24:25], v[24:25], 2, s[2:3]
	global_load_dword v46, v[26:27], off
	global_load_dword v47, v[24:25], off
	v_mad_u64_u32 v[68:69], s[46:47], v23, s81, v[6:7]
	v_mad_u64_u32 v[70:71], s[46:47], v21, s81, v[6:7]
	s_add_i32 s46, s29, 16
	s_add_i32 s47, s45, 16
	v_or_b32_e32 v21, s46, v3
	v_or_b32_e32 v23, s47, v2
	v_add_lshl_u32 v25, v23, s16, 10
	v_add_lshl_u32 v0, v21, s20, 10
	v_or_b32_e32 v24, v5, v0
	v_or_b32_e32 v0, v22, v25
	v_lshl_add_u64 v[26:27], v[0:1], 2, s[2:3]
	v_mov_b32_e32 v25, v1
	v_lshl_add_u64 v[24:25], v[24:25], 2, s[2:3]
	global_load_dword v48, v[26:27], off
	global_load_dword v49, v[24:25], off
	v_mad_u64_u32 v[72:73], s[46:47], v23, s81, v[6:7]
	v_mad_u64_u32 v[74:75], s[46:47], v21, s81, v[6:7]
	s_add_i32 s46, s29, 20
	s_add_i32 s47, s45, 20
	v_or_b32_e32 v21, s46, v3
	v_or_b32_e32 v23, s47, v2
	v_add_lshl_u32 v25, v23, s16, 10
	v_add_lshl_u32 v0, v21, s20, 10
	v_or_b32_e32 v24, v5, v0
	v_or_b32_e32 v0, v22, v25
	v_lshl_add_u64 v[26:27], v[0:1], 2, s[2:3]
	v_mov_b32_e32 v25, v1
	v_lshl_add_u64 v[24:25], v[24:25], 2, s[2:3]
	global_load_dword v50, v[26:27], off
	global_load_dword v51, v[24:25], off
	v_mad_u64_u32 v[76:77], s[46:47], v23, s81, v[6:7]
	v_mad_u64_u32 v[78:79], s[46:47], v21, s81, v[6:7]
	s_add_i32 s46, s29, 24
	s_add_i32 s47, s45, 24
	v_or_b32_e32 v21, s46, v3
	v_or_b32_e32 v23, s47, v2
	v_add_lshl_u32 v25, v23, s16, 10
	s_add_i32 s29, s29, 28
	s_add_i32 s45, s45, 28
	s_cmp_lg_u32 s28, 0
	v_add_lshl_u32 v0, v21, s20, 10
	v_or_b32_e32 v24, v5, v0
	v_or_b32_e32 v0, v22, v25
	v_lshl_add_u64 v[26:27], v[0:1], 2, s[2:3]
	v_mov_b32_e32 v25, v1
	v_lshl_add_u64 v[24:25], v[24:25], 2, s[2:3]
	global_load_dword v52, v[26:27], off
	global_load_dword v53, v[24:25], off
	v_mad_u64_u32 v[80:81], s[46:47], v23, s81, v[6:7]
	v_mad_u64_u32 v[82:83], s[46:47], v21, s81, v[6:7]
	v_or_b32_e32 v21, s29, v3
	v_or_b32_e32 v23, s45, v2
	v_mov_b32_e32 v27, v1
	v_add_lshl_u32 v0, v21, s20, 10
	v_add_lshl_u32 v24, v23, s16, 10
	v_or_b32_e32 v26, v5, v0
	v_or_b32_e32 v0, v22, v24
	v_lshl_add_u64 v[24:25], v[0:1], 2, s[2:3]
	v_lshl_add_u64 v[26:27], v[26:27], 2, s[2:3]
	global_load_dword v54, v[24:25], off
	global_load_dword v55, v[26:27], off
	v_mad_u64_u32 v[84:85], s[46:47], v23, s81, v[6:7]
	v_mad_u64_u32 v[86:87], s[46:47], v21, s81, v[6:7]
	s_waitcnt vmcnt(15)
	ds_write_b32 v56, v40
	s_waitcnt vmcnt(14)
	ds_write_b32 v58, v41
	s_waitcnt vmcnt(13)
	ds_write_b32 v60, v42
	s_waitcnt vmcnt(12)
	ds_write_b32 v62, v43
	s_waitcnt vmcnt(11)
	ds_write_b32 v64, v44
	s_waitcnt vmcnt(10)
	ds_write_b32 v66, v45
	s_waitcnt vmcnt(9)
	ds_write_b32 v68, v46
	s_waitcnt vmcnt(8)
	ds_write_b32 v70, v47
	s_waitcnt vmcnt(7)
	ds_write_b32 v72, v48
	s_waitcnt vmcnt(6)
	ds_write_b32 v74, v49
	s_waitcnt vmcnt(5)
	ds_write_b32 v76, v50
	s_waitcnt vmcnt(4)
	ds_write_b32 v78, v51
	s_waitcnt vmcnt(3)
	ds_write_b32 v80, v52
	s_waitcnt vmcnt(2)
	ds_write_b32 v82, v53
	s_waitcnt vmcnt(1)
	ds_write_b32 v84, v54
	s_waitcnt vmcnt(0)
	ds_write_b32 v86, v55
	s_cbranch_scc1 .LBB0_72
	s_waitcnt lgkmcnt(0)
	ds_read2_b32 v[24:25], v28 offset1:33
	s_waitcnt lgkmcnt(0)
	v_cvt_pk_bf16_f32 v24, v24, v25
	ds_read2_b32 v[26:27], v28 offset0:66 offset1:99
	v_or_b32_e32 v0, s10, v7
	s_lshl_b32 s16, s16, 1
	s_waitcnt lgkmcnt(0)
	v_cvt_pk_bf16_f32 v25, v26, v27
	ds_read2_b32 v[26:27], v28 offset0:132 offset1:165
	v_mul_u32_u24_e32 v0, 0xb00, v0
	v_lshl_add_u64 v[22:23], v[10:11], 0, s[16:17]
	s_waitcnt lgkmcnt(0)
	v_cvt_pk_bf16_f32 v26, v26, v27
	ds_read2_b32 v[36:37], v28 offset0:198 offset1:231
	v_lshlrev_b32_e32 v0, 1, v0
	s_waitcnt lgkmcnt(0)
	v_cvt_pk_bf16_f32 v27, v36, v37
	v_lshl_add_u64 v[36:37], v[22:23], 0, v[0:1]
	global_store_dwordx4 v[36:37], v[24:27], off
	ds_read2_b32 v[24:25], v28 offset0:8 offset1:41
	v_or_b32_e32 v0, s10, v29
	s_waitcnt lgkmcnt(0)
	v_cvt_pk_bf16_f32 v24, v24, v25
	ds_read2_b32 v[26:27], v28 offset0:74 offset1:107
	s_waitcnt lgkmcnt(0)
	v_cvt_pk_bf16_f32 v25, v26, v27
	ds_read2_b32 v[26:27], v28 offset0:140 offset1:173
	v_mul_u32_u24_e32 v0, 0xb00, v0
	s_waitcnt lgkmcnt(0)
	v_cvt_pk_bf16_f32 v26, v26, v27
	ds_read2_b32 v[36:37], v28 offset0:206 offset1:239
	v_lshlrev_b32_e32 v0, 1, v0
	s_waitcnt lgkmcnt(0)
	v_cvt_pk_bf16_f32 v27, v36, v37
	v_lshl_add_u64 v[36:37], v[22:23], 0, v[0:1]
	global_store_dwordx4 v[36:37], v[24:27], off
	ds_read2_b32 v[24:25], v28 offset0:16 offset1:49
	v_or_b32_e32 v0, s10, v30
	s_waitcnt lgkmcnt(0)
	v_cvt_pk_bf16_f32 v24, v24, v25
	ds_read2_b32 v[26:27], v28 offset0:82 offset1:115
	s_waitcnt lgkmcnt(0)
	v_cvt_pk_bf16_f32 v25, v26, v27
	ds_read2_b32 v[26:27], v28 offset0:148 offset1:181
	v_mul_u32_u24_e32 v0, 0xb00, v0
	s_waitcnt lgkmcnt(0)
	v_cvt_pk_bf16_f32 v26, v26, v27
	ds_read2_b32 v[36:37], v28 offset0:214 offset1:247
	v_lshlrev_b32_e32 v0, 1, v0
	s_waitcnt lgkmcnt(0)
	v_cvt_pk_bf16_f32 v27, v36, v37
	v_lshl_add_u64 v[36:37], v[22:23], 0, v[0:1]
	v_or_b32_e32 v0, s10, v31
	global_store_dwordx4 v[36:37], v[24:27], off
	ds_read2_b32 v[24:25], v28 offset0:24 offset1:57
	v_mul_u32_u24_e32 v0, 0xb00, v0
	s_waitcnt lgkmcnt(0)
	v_cvt_pk_bf16_f32 v24, v24, v25
	ds_read2_b32 v[26:27], v28 offset0:90 offset1:123
	v_lshlrev_b32_e32 v0, 1, v0
	s_waitcnt lgkmcnt(0)
	v_cvt_pk_bf16_f32 v25, v26, v27
	ds_read2_b32 v[26:27], v28 offset0:156 offset1:189
	v_lshl_add_u64 v[22:23], v[22:23], 0, v[0:1]
	s_waitcnt lgkmcnt(0)
	v_cvt_pk_bf16_f32 v26, v26, v27
	ds_read2_b32 v[36:37], v28 offset0:222 offset1:255
	s_waitcnt lgkmcnt(0)
	v_cvt_pk_bf16_f32 v27, v36, v37
	global_store_dwordx4 v[22:23], v[24:27], off
	s_waitcnt lgkmcnt(0)
	s_movk_i32 s10, 0x3bf
	s_mov_b64 s[20:21], 0x200

.LBB0_77:
	s_lshl_b32 s45, s21, 1
	s_lshl_b32 s29, s20, 1
	v_or_b32_e32 v21, s45, v2
	v_or_b32_e32 v5, s29, v3
	v_add_u32_e32 v24, s10, v21
	v_add_u32_e32 v22, s16, v5
	v_mad_u64_u32 v[24:25], s[46:47], v24, s54, v[0:1]
	v_mad_u64_u32 v[22:23], s[46:47], v22, s54, v[0:1]
	v_mov_b32_e32 v25, v1
	v_lshl_add_u64 v[24:25], v[24:25], 2, s[2:3]
	v_mov_b32_e32 v23, v1
	v_lshl_add_u64 v[22:23], v[22:23], 2, s[2:3]
	global_load_dword v40, v[24:25], off
	global_load_dword v41, v[22:23], off
	v_mad_u64_u32 v[56:57], s[46:47], v21, s81, v[6:7]
	v_mad_u64_u32 v[58:59], s[46:47], v5, s81, v[6:7]
	s_add_i32 s47, s45, 4
	s_add_i32 s46, s29, 4
	v_or_b32_e32 v21, s47, v2
	v_or_b32_e32 v5, s46, v3
	s_add_i32 s21, s21, 16
	s_add_i32 s20, s20, 16
	s_add_i32 s28, s28, -16
	v_add_u32_e32 v24, s10, v21
	v_add_u32_e32 v22, s16, v5
	v_mad_u64_u32 v[24:25], s[46:47], v24, s54, v[0:1]
	v_mad_u64_u32 v[22:23], s[46:47], v22, s54, v[0:1]
	v_mov_b32_e32 v25, v1
	v_lshl_add_u64 v[24:25], v[24:25], 2, s[2:3]
	v_mov_b32_e32 v23, v1
	v_lshl_add_u64 v[22:23], v[22:23], 2, s[2:3]
	global_load_dword v42, v[24:25], off
	global_load_dword v43, v[22:23], off
	v_mad_u64_u32 v[60:61], s[46:47], v21, s81, v[6:7]
	v_mad_u64_u32 v[62:63], s[46:47], v5, s81, v[6:7]
	s_add_i32 s47, s45, 8
	s_add_i32 s46, s29, 8
	v_or_b32_e32 v21, s47, v2
	v_or_b32_e32 v5, s46, v3
	v_add_u32_e32 v24, s10, v21
	v_add_u32_e32 v22, s16, v5
	v_mad_u64_u32 v[24:25], s[46:47], v24, s54, v[0:1]
	v_mad_u64_u32 v[22:23], s[46:47], v22, s54, v[0:1]
	v_mov_b32_e32 v25, v1
	v_lshl_add_u64 v[24:25], v[24:25], 2, s[2:3]
	v_mov_b32_e32 v23, v1
	v_lshl_add_u64 v[22:23], v[22:23], 2, s[2:3]
	global_load_dword v44, v[24:25], off
	global_load_dword v45, v[22:23], off
	v_mad_u64_u32 v[64:65], s[46:47], v21, s81, v[6:7]
	v_mad_u64_u32 v[66:67], s[46:47], v5, s81, v[6:7]
	s_add_i32 s47, s45, 12
	s_add_i32 s46, s29, 12
	v_or_b32_e32 v21, s47, v2
	v_or_b32_e32 v5, s46, v3
	v_add_u32_e32 v24, s10, v21
	v_add_u32_e32 v22, s16, v5
	v_mad_u64_u32 v[24:25], s[46:47], v24, s54, v[0:1]
	v_mad_u64_u32 v[22:23], s[46:47], v22, s54, v[0:1]
	v_mov_b32_e32 v25, v1
	v_lshl_add_u64 v[24:25], v[24:25], 2, s[2:3]
	v_mov_b32_e32 v23, v1
	v_lshl_add_u64 v[22:23], v[22:23], 2, s[2:3]
	global_load_dword v46, v[24:25], off
	global_load_dword v47, v[22:23], off
	v_mad_u64_u32 v[68:69], s[46:47], v21, s81, v[6:7]
	v_mad_u64_u32 v[70:71], s[46:47], v5, s81, v[6:7]
	s_add_i32 s47, s45, 16
	s_add_i32 s46, s29, 16
	v_or_b32_e32 v21, s47, v2
	v_or_b32_e32 v5, s46, v3
	v_add_u32_e32 v24, s10, v21
	v_add_u32_e32 v22, s16, v5
	v_mad_u64_u32 v[24:25], s[46:47], v24, s54, v[0:1]
	v_mad_u64_u32 v[22:23], s[46:47], v22, s54, v[0:1]
	v_mov_b32_e32 v25, v1
	v_lshl_add_u64 v[24:25], v[24:25], 2, s[2:3]
	v_mov_b32_e32 v23, v1
	v_lshl_add_u64 v[22:23], v[22:23], 2, s[2:3]
	global_load_dword v48, v[24:25], off
	global_load_dword v49, v[22:23], off
	v_mad_u64_u32 v[72:73], s[46:47], v21, s81, v[6:7]
	v_mad_u64_u32 v[74:75], s[46:47], v5, s81, v[6:7]
	s_add_i32 s47, s45, 20
	s_add_i32 s46, s29, 20
	v_or_b32_e32 v21, s47, v2
	v_or_b32_e32 v5, s46, v3
	v_add_u32_e32 v24, s10, v21
	v_add_u32_e32 v22, s16, v5
	v_mad_u64_u32 v[24:25], s[46:47], v24, s54, v[0:1]
	v_mad_u64_u32 v[22:23], s[46:47], v22, s54, v[0:1]
	v_mov_b32_e32 v25, v1
	v_lshl_add_u64 v[24:25], v[24:25], 2, s[2:3]
	v_mov_b32_e32 v23, v1
	v_lshl_add_u64 v[22:23], v[22:23], 2, s[2:3]
	global_load_dword v50, v[24:25], off
	global_load_dword v51, v[22:23], off
	v_mad_u64_u32 v[76:77], s[46:47], v21, s81, v[6:7]
	v_mad_u64_u32 v[78:79], s[46:47], v5, s81, v[6:7]
	s_add_i32 s47, s45, 24
	s_add_i32 s46, s29, 24
	v_or_b32_e32 v21, s47, v2
	v_or_b32_e32 v5, s46, v3
	s_add_i32 s45, s45, 28
	s_add_i32 s29, s29, 28
	s_cmp_lg_u32 s28, 0
	v_add_u32_e32 v24, s10, v21
	v_add_u32_e32 v22, s16, v5
	v_mad_u64_u32 v[24:25], s[46:47], v24, s54, v[0:1]
	v_mad_u64_u32 v[22:23], s[46:47], v22, s54, v[0:1]
	v_mov_b32_e32 v25, v1
	v_lshl_add_u64 v[24:25], v[24:25], 2, s[2:3]
	v_mov_b32_e32 v23, v1
	v_lshl_add_u64 v[22:23], v[22:23], 2, s[2:3]
	global_load_dword v52, v[24:25], off
	global_load_dword v53, v[22:23], off
	v_mad_u64_u32 v[80:81], s[46:47], v21, s81, v[6:7]
	v_mad_u64_u32 v[82:83], s[46:47], v5, s81, v[6:7]
	v_or_b32_e32 v21, s45, v2
	v_or_b32_e32 v5, s29, v3
	v_add_u32_e32 v24, s10, v21
	v_add_u32_e32 v22, s16, v5
	v_mad_u64_u32 v[24:25], s[46:47], v24, s54, v[0:1]
	v_mad_u64_u32 v[22:23], s[46:47], v22, s54, v[0:1]
	v_mov_b32_e32 v25, v1
	v_lshl_add_u64 v[24:25], v[24:25], 2, s[2:3]
	v_mov_b32_e32 v23, v1
	v_lshl_add_u64 v[22:23], v[22:23], 2, s[2:3]
	global_load_dword v54, v[24:25], off
	global_load_dword v55, v[22:23], off
	v_mad_u64_u32 v[84:85], s[46:47], v21, s81, v[6:7]
	v_mad_u64_u32 v[86:87], s[46:47], v5, s81, v[6:7]
	s_waitcnt vmcnt(15)
	ds_write_b32 v56, v40
	s_waitcnt vmcnt(14)
	ds_write_b32 v58, v41
	s_waitcnt vmcnt(13)
	ds_write_b32 v60, v42
	s_waitcnt vmcnt(12)
	ds_write_b32 v62, v43
	s_waitcnt vmcnt(11)
	ds_write_b32 v64, v44
	s_waitcnt vmcnt(10)
	ds_write_b32 v66, v45
	s_waitcnt vmcnt(9)
	ds_write_b32 v68, v46
	s_waitcnt vmcnt(8)
	ds_write_b32 v70, v47
	s_waitcnt vmcnt(7)
	ds_write_b32 v72, v48
	s_waitcnt vmcnt(6)
	ds_write_b32 v74, v49
	s_waitcnt vmcnt(5)
	ds_write_b32 v76, v50
	s_waitcnt vmcnt(4)
	ds_write_b32 v78, v51
	s_waitcnt vmcnt(3)
	ds_write_b32 v80, v52
	s_waitcnt vmcnt(2)
	ds_write_b32 v82, v53
	s_waitcnt vmcnt(1)
	ds_write_b32 v84, v54
	s_waitcnt vmcnt(0)
	ds_write_b32 v86, v55
	s_cbranch_scc1 .LBB0_77
	s_waitcnt lgkmcnt(0)
	s_lshl_b32 s2, s11, 1
	s_and_b32 s2, s2, 0x1f00
	s_and_b32 s3, s11, 0x60
	ds_read2_b32 v[22:23], v28 offset1:33
	s_or_b32 s2, s2, s3
	s_waitcnt lgkmcnt(0)
	v_cvt_pk_bf16_f32 v22, v22, v23
	ds_read2_b32 v[24:25], v28 offset0:66 offset1:99
	s_waitcnt lgkmcnt(0)
	v_cvt_pk_bf16_f32 v23, v24, v25
	ds_read2_b32 v[24:25], v28 offset0:132 offset1:165
	v_or_b32_e32 v0, s2, v7
	s_waitcnt lgkmcnt(0)
	v_cvt_pk_bf16_f32 v24, v24, v25
	ds_read2_b32 v[26:27], v28 offset0:198 offset1:231
	v_lshlrev_b32_e32 v0, 11, v0
	s_and_b32 s3, 0xffff, s10
	s_waitcnt lgkmcnt(0)
	v_cvt_pk_bf16_f32 v25, v26, v27
	v_lshl_add_u64 v[26:27], s[40:41], 0, v[0:1]
	s_lshl_b32 s16, s3, 1
	v_lshl_add_u64 v[26:27], v[26:27], 0, s[16:17]
	v_mov_b32_e32 v21, v1
	v_lshl_add_u64 v[26:27], v[26:27], 0, v[20:21]
	s_mov_b32 s3, 0x40000
	v_add_co_u32_e32 v26, vcc, s3, v26
	v_or_b32_e32 v0, s2, v29
	s_nop 0
	v_addc_co_u32_e32 v27, vcc, 0, v27, vcc
	global_store_dwordx4 v[26:27], v[22:25], off
	ds_read2_b32 v[22:23], v28 offset0:8 offset1:41
	v_lshlrev_b32_e32 v0, 11, v0
	s_waitcnt lgkmcnt(0)
	v_cvt_pk_bf16_f32 v22, v22, v23
	ds_read2_b32 v[24:25], v28 offset0:74 offset1:107
	s_waitcnt lgkmcnt(0)
	v_cvt_pk_bf16_f32 v23, v24, v25
	ds_read2_b32 v[24:25], v28 offset0:140 offset1:173
	s_waitcnt lgkmcnt(0)
	v_cvt_pk_bf16_f32 v24, v24, v25
	ds_read2_b32 v[26:27], v28 offset0:206 offset1:239
	s_waitcnt lgkmcnt(0)
	v_cvt_pk_bf16_f32 v25, v26, v27
	v_lshl_add_u64 v[26:27], s[40:41], 0, v[0:1]
	v_lshl_add_u64 v[26:27], v[26:27], 0, s[16:17]
	v_lshl_add_u64 v[26:27], v[26:27], 0, v[20:21]
	v_add_co_u32_e32 v26, vcc, s3, v26
	v_or_b32_e32 v0, s2, v30
	s_nop 0
	v_addc_co_u32_e32 v27, vcc, 0, v27, vcc
	global_store_dwordx4 v[26:27], v[22:25], off
	ds_read2_b32 v[22:23], v28 offset0:16 offset1:49
	v_lshlrev_b32_e32 v0, 11, v0
	s_waitcnt lgkmcnt(0)
	v_cvt_pk_bf16_f32 v22, v22, v23
	ds_read2_b32 v[24:25], v28 offset0:82 offset1:115
	s_waitcnt lgkmcnt(0)
	v_cvt_pk_bf16_f32 v23, v24, v25
	ds_read2_b32 v[24:25], v28 offset0:148 offset1:181
	s_waitcnt lgkmcnt(0)
	v_cvt_pk_bf16_f32 v24, v24, v25
	ds_read2_b32 v[26:27], v28 offset0:214 offset1:247
	s_waitcnt lgkmcnt(0)
	v_cvt_pk_bf16_f32 v25, v26, v27
	v_lshl_add_u64 v[26:27], s[40:41], 0, v[0:1]
	v_lshl_add_u64 v[26:27], v[26:27], 0, s[16:17]
	v_lshl_add_u64 v[26:27], v[26:27], 0, v[20:21]
	v_add_co_u32_e32 v26, vcc, s3, v26
	v_or_b32_e32 v0, s2, v31
	s_nop 0
	v_addc_co_u32_e32 v27, vcc, 0, v27, vcc
	global_store_dwordx4 v[26:27], v[22:25], off
	ds_read2_b32 v[22:23], v28 offset0:24 offset1:57
	v_lshlrev_b32_e32 v0, 11, v0
	s_waitcnt lgkmcnt(0)
	v_cvt_pk_bf16_f32 v22, v22, v23
	ds_read2_b32 v[24:25], v28 offset0:90 offset1:123
	s_waitcnt lgkmcnt(0)
	v_cvt_pk_bf16_f32 v23, v24, v25
	ds_read2_b32 v[24:25], v28 offset0:156 offset1:189
	s_waitcnt lgkmcnt(0)
	v_cvt_pk_bf16_f32 v24, v24, v25
	ds_read2_b32 v[26:27], v28 offset0:222 offset1:255
	s_waitcnt lgkmcnt(0)
	v_cvt_pk_bf16_f32 v25, v26, v27
	v_lshl_add_u64 v[26:27], s[40:41], 0, v[0:1]
	v_lshl_add_u64 v[26:27], v[26:27], 0, s[16:17]
	v_lshl_add_u64 v[26:27], v[26:27], 0, v[20:21]
	v_add_co_u32_e32 v26, vcc, 0x40000, v26
	s_movk_i32 s10, 0x3bf
	s_nop 0
	v_addc_co_u32_e32 v27, vcc, 0, v27, vcc
	global_store_dwordx4 v[26:27], v[22:25], off
	s_waitcnt lgkmcnt(0)
	s_mov_b64 s[20:21], 0x200

.LBB0_82:
	s_lshl_b32 s45, s21, 1
	s_lshl_b32 s29, s20, 1
	v_or_b32_e32 v21, s45, v2
	v_or_b32_e32 v5, s29, v3
	v_add_u32_e32 v24, s10, v21
	v_add_u32_e32 v22, s16, v5
	v_mad_u64_u32 v[24:25], s[46:47], v24, s54, v[0:1]
	v_mad_u64_u32 v[22:23], s[46:47], v22, s54, v[0:1]
	v_mov_b32_e32 v25, v1
	v_lshl_add_u64 v[24:25], v[24:25], 2, s[2:3]
	v_mov_b32_e32 v23, v1
	v_lshl_add_u64 v[22:23], v[22:23], 2, s[2:3]
	global_load_dword v40, v[24:25], off
	global_load_dword v41, v[22:23], off
	v_mad_u64_u32 v[56:57], s[46:47], v21, s81, v[6:7]
	v_mad_u64_u32 v[58:59], s[46:47], v5, s81, v[6:7]
	s_add_i32 s47, s45, 4
	s_add_i32 s46, s29, 4
	v_or_b32_e32 v21, s47, v2
	v_or_b32_e32 v5, s46, v3
	s_add_i32 s21, s21, 16
	s_add_i32 s20, s20, 16
	s_add_i32 s28, s28, -16
	v_add_u32_e32 v24, s10, v21
	v_add_u32_e32 v22, s16, v5
	v_mad_u64_u32 v[24:25], s[46:47], v24, s54, v[0:1]
	v_mad_u64_u32 v[22:23], s[46:47], v22, s54, v[0:1]
	v_mov_b32_e32 v25, v1
	v_lshl_add_u64 v[24:25], v[24:25], 2, s[2:3]
	v_mov_b32_e32 v23, v1
	v_lshl_add_u64 v[22:23], v[22:23], 2, s[2:3]
	global_load_dword v42, v[24:25], off
	global_load_dword v43, v[22:23], off
	v_mad_u64_u32 v[60:61], s[46:47], v21, s81, v[6:7]
	v_mad_u64_u32 v[62:63], s[46:47], v5, s81, v[6:7]
	s_add_i32 s47, s45, 8
	s_add_i32 s46, s29, 8
	v_or_b32_e32 v21, s47, v2
	v_or_b32_e32 v5, s46, v3
	v_add_u32_e32 v24, s10, v21
	v_add_u32_e32 v22, s16, v5
	v_mad_u64_u32 v[24:25], s[46:47], v24, s54, v[0:1]
	v_mad_u64_u32 v[22:23], s[46:47], v22, s54, v[0:1]
	v_mov_b32_e32 v25, v1
	v_lshl_add_u64 v[24:25], v[24:25], 2, s[2:3]
	v_mov_b32_e32 v23, v1
	v_lshl_add_u64 v[22:23], v[22:23], 2, s[2:3]
	global_load_dword v44, v[24:25], off
	global_load_dword v45, v[22:23], off
	v_mad_u64_u32 v[64:65], s[46:47], v21, s81, v[6:7]
	v_mad_u64_u32 v[66:67], s[46:47], v5, s81, v[6:7]
	s_add_i32 s47, s45, 12
	s_add_i32 s46, s29, 12
	v_or_b32_e32 v21, s47, v2
	v_or_b32_e32 v5, s46, v3
	v_add_u32_e32 v24, s10, v21
	v_add_u32_e32 v22, s16, v5
	v_mad_u64_u32 v[24:25], s[46:47], v24, s54, v[0:1]
	v_mad_u64_u32 v[22:23], s[46:47], v22, s54, v[0:1]
	v_mov_b32_e32 v25, v1
	v_lshl_add_u64 v[24:25], v[24:25], 2, s[2:3]
	v_mov_b32_e32 v23, v1
	v_lshl_add_u64 v[22:23], v[22:23], 2, s[2:3]
	global_load_dword v46, v[24:25], off
	global_load_dword v47, v[22:23], off
	v_mad_u64_u32 v[68:69], s[46:47], v21, s81, v[6:7]
	v_mad_u64_u32 v[70:71], s[46:47], v5, s81, v[6:7]
	s_add_i32 s47, s45, 16
	s_add_i32 s46, s29, 16
	v_or_b32_e32 v21, s47, v2
	v_or_b32_e32 v5, s46, v3
	v_add_u32_e32 v24, s10, v21
	v_add_u32_e32 v22, s16, v5
	v_mad_u64_u32 v[24:25], s[46:47], v24, s54, v[0:1]
	v_mad_u64_u32 v[22:23], s[46:47], v22, s54, v[0:1]
	v_mov_b32_e32 v25, v1
	v_lshl_add_u64 v[24:25], v[24:25], 2, s[2:3]
	v_mov_b32_e32 v23, v1
	v_lshl_add_u64 v[22:23], v[22:23], 2, s[2:3]
	global_load_dword v48, v[24:25], off
	global_load_dword v49, v[22:23], off
	v_mad_u64_u32 v[72:73], s[46:47], v21, s81, v[6:7]
	v_mad_u64_u32 v[74:75], s[46:47], v5, s81, v[6:7]
	s_add_i32 s47, s45, 20
	s_add_i32 s46, s29, 20
	v_or_b32_e32 v21, s47, v2
	v_or_b32_e32 v5, s46, v3
	v_add_u32_e32 v24, s10, v21
	v_add_u32_e32 v22, s16, v5
	v_mad_u64_u32 v[24:25], s[46:47], v24, s54, v[0:1]
	v_mad_u64_u32 v[22:23], s[46:47], v22, s54, v[0:1]
	v_mov_b32_e32 v25, v1
	v_lshl_add_u64 v[24:25], v[24:25], 2, s[2:3]
	v_mov_b32_e32 v23, v1
	v_lshl_add_u64 v[22:23], v[22:23], 2, s[2:3]
	global_load_dword v50, v[24:25], off
	global_load_dword v51, v[22:23], off
	v_mad_u64_u32 v[76:77], s[46:47], v21, s81, v[6:7]
	v_mad_u64_u32 v[78:79], s[46:47], v5, s81, v[6:7]
	s_add_i32 s47, s45, 24
	s_add_i32 s46, s29, 24
	v_or_b32_e32 v21, s47, v2
	v_or_b32_e32 v5, s46, v3
	s_add_i32 s45, s45, 28
	s_add_i32 s29, s29, 28
	s_cmp_lg_u32 s28, 0
	v_add_u32_e32 v24, s10, v21
	v_add_u32_e32 v22, s16, v5
	v_mad_u64_u32 v[24:25], s[46:47], v24, s54, v[0:1]
	v_mad_u64_u32 v[22:23], s[46:47], v22, s54, v[0:1]
	v_mov_b32_e32 v25, v1
	v_lshl_add_u64 v[24:25], v[24:25], 2, s[2:3]
	v_mov_b32_e32 v23, v1
	v_lshl_add_u64 v[22:23], v[22:23], 2, s[2:3]
	global_load_dword v52, v[24:25], off
	global_load_dword v53, v[22:23], off
	v_mad_u64_u32 v[80:81], s[46:47], v21, s81, v[6:7]
	v_mad_u64_u32 v[82:83], s[46:47], v5, s81, v[6:7]
	v_or_b32_e32 v21, s45, v2
	v_or_b32_e32 v5, s29, v3
	v_add_u32_e32 v24, s10, v21
	v_add_u32_e32 v22, s16, v5
	v_mad_u64_u32 v[24:25], s[46:47], v24, s54, v[0:1]
	v_mad_u64_u32 v[22:23], s[46:47], v22, s54, v[0:1]
	v_mov_b32_e32 v25, v1
	v_lshl_add_u64 v[24:25], v[24:25], 2, s[2:3]
	v_mov_b32_e32 v23, v1
	v_lshl_add_u64 v[22:23], v[22:23], 2, s[2:3]
	global_load_dword v54, v[24:25], off
	global_load_dword v55, v[22:23], off
	v_mad_u64_u32 v[84:85], s[46:47], v21, s81, v[6:7]
	v_mad_u64_u32 v[86:87], s[46:47], v5, s81, v[6:7]
	s_waitcnt vmcnt(15)
	ds_write_b32 v56, v40
	s_waitcnt vmcnt(14)
	ds_write_b32 v58, v41
	s_waitcnt vmcnt(13)
	ds_write_b32 v60, v42
	s_waitcnt vmcnt(12)
	ds_write_b32 v62, v43
	s_waitcnt vmcnt(11)
	ds_write_b32 v64, v44
	s_waitcnt vmcnt(10)
	ds_write_b32 v66, v45
	s_waitcnt vmcnt(9)
	ds_write_b32 v68, v46
	s_waitcnt vmcnt(8)
	ds_write_b32 v70, v47
	s_waitcnt vmcnt(7)
	ds_write_b32 v72, v48
	s_waitcnt vmcnt(6)
	ds_write_b32 v74, v49
	s_waitcnt vmcnt(5)
	ds_write_b32 v76, v50
	s_waitcnt vmcnt(4)
	ds_write_b32 v78, v51
	s_waitcnt vmcnt(3)
	ds_write_b32 v80, v52
	s_waitcnt vmcnt(2)
	ds_write_b32 v82, v53
	s_waitcnt vmcnt(1)
	ds_write_b32 v84, v54
	s_waitcnt vmcnt(0)
	ds_write_b32 v86, v55
	s_cbranch_scc1 .LBB0_82
	s_waitcnt lgkmcnt(0)
	s_lshl_b32 s2, s11, 1
	s_and_b32 s2, s2, 0x1f00
	s_and_b32 s3, s11, 0x60
	ds_read2_b32 v[24:25], v28 offset1:33
	s_or_b32 s2, s2, s3
	s_and_b32 s3, 0xffff, s10
	s_waitcnt lgkmcnt(0)
	v_cvt_pk_bf16_f32 v24, v24, v25
	ds_read2_b32 v[26:27], v28 offset0:66 offset1:99
	s_lshl_b32 s16, s3, 1
	s_waitcnt lgkmcnt(0)
	v_cvt_pk_bf16_f32 v25, v26, v27
	ds_read2_b32 v[26:27], v28 offset0:132 offset1:165
	v_or_b32_e32 v0, s2, v7
	v_lshl_add_u64 v[22:23], v[12:13], 0, s[16:17]
	s_waitcnt lgkmcnt(0)
	v_cvt_pk_bf16_f32 v26, v26, v27
	ds_read2_b32 v[36:37], v28 offset0:198 offset1:231
	v_lshlrev_b32_e32 v0, 11, v0
	s_waitcnt lgkmcnt(0)
	v_cvt_pk_bf16_f32 v27, v36, v37
	v_lshl_add_u64 v[36:37], v[22:23], 0, v[0:1]
	global_store_dwordx4 v[36:37], v[24:27], off
	ds_read2_b32 v[24:25], v28 offset0:8 offset1:41
	v_or_b32_e32 v0, s2, v29
	s_waitcnt lgkmcnt(0)
	v_cvt_pk_bf16_f32 v24, v24, v25
	ds_read2_b32 v[26:27], v28 offset0:74 offset1:107
	s_waitcnt lgkmcnt(0)
	v_cvt_pk_bf16_f32 v25, v26, v27
	ds_read2_b32 v[26:27], v28 offset0:140 offset1:173
	s_waitcnt lgkmcnt(0)
	v_cvt_pk_bf16_f32 v26, v26, v27
	ds_read2_b32 v[36:37], v28 offset0:206 offset1:239
	v_lshlrev_b32_e32 v0, 11, v0
	s_waitcnt lgkmcnt(0)
	v_cvt_pk_bf16_f32 v27, v36, v37
	v_lshl_add_u64 v[36:37], v[22:23], 0, v[0:1]
	global_store_dwordx4 v[36:37], v[24:27], off
	ds_read2_b32 v[24:25], v28 offset0:16 offset1:49
	v_or_b32_e32 v0, s2, v30
	s_waitcnt lgkmcnt(0)
	v_cvt_pk_bf16_f32 v24, v24, v25
	ds_read2_b32 v[26:27], v28 offset0:82 offset1:115
	s_waitcnt lgkmcnt(0)
	v_cvt_pk_bf16_f32 v25, v26, v27
	ds_read2_b32 v[26:27], v28 offset0:148 offset1:181
	s_waitcnt lgkmcnt(0)
	v_cvt_pk_bf16_f32 v26, v26, v27
	ds_read2_b32 v[36:37], v28 offset0:214 offset1:247
	v_lshlrev_b32_e32 v0, 11, v0
	s_waitcnt lgkmcnt(0)
	v_cvt_pk_bf16_f32 v27, v36, v37
	v_lshl_add_u64 v[36:37], v[22:23], 0, v[0:1]
	global_store_dwordx4 v[36:37], v[24:27], off
	ds_read2_b32 v[24:25], v28 offset0:24 offset1:57
	v_or_b32_e32 v0, s2, v31
	s_waitcnt lgkmcnt(0)
	v_cvt_pk_bf16_f32 v24, v24, v25
	ds_read2_b32 v[26:27], v28 offset0:90 offset1:123
	v_lshlrev_b32_e32 v0, 11, v0
	s_waitcnt lgkmcnt(0)
	v_cvt_pk_bf16_f32 v25, v26, v27
	ds_read2_b32 v[26:27], v28 offset0:156 offset1:189
	v_lshl_add_u64 v[22:23], v[22:23], 0, v[0:1]
	s_waitcnt lgkmcnt(0)
	v_cvt_pk_bf16_f32 v26, v26, v27
	ds_read2_b32 v[36:37], v28 offset0:222 offset1:255
	s_waitcnt lgkmcnt(0)
	v_cvt_pk_bf16_f32 v27, v36, v37
	global_store_dwordx4 v[22:23], v[24:27], off
	s_waitcnt lgkmcnt(0)
	s_movk_i32 s10, 0x3bf
	s_mov_b64 s[20:21], 0x200

.LBB0_87:
	s_lshl_b32 s29, s11, 1
	s_lshl_b32 s45, s21, 1
	v_or_b32_e32 v21, s29, v3
	v_or_b32_e32 v23, s45, v2
	v_add_lshl_u32 v0, v21, s20, 10
	v_add_lshl_u32 v25, v23, s16, 10
	v_or_b32_e32 v24, v5, v0
	v_or_b32_e32 v0, v22, v25
	v_lshl_add_u64 v[26:27], v[0:1], 2, s[2:3]
	v_mov_b32_e32 v25, v1
	v_lshl_add_u64 v[24:25], v[24:25], 2, s[2:3]
	global_load_dword v40, v[26:27], off
	global_load_dword v41, v[24:25], off
	v_mad_u64_u32 v[56:57], s[46:47], v23, s81, v[6:7]
	v_mad_u64_u32 v[58:59], s[46:47], v21, s81, v[6:7]
	s_add_i32 s46, s29, 4
	s_add_i32 s47, s45, 4
	v_or_b32_e32 v21, s46, v3
	v_or_b32_e32 v23, s47, v2
	v_add_lshl_u32 v25, v23, s16, 10
	s_add_i32 s21, s21, 16
	s_add_i32 s11, s11, 16
	s_add_i32 s28, s28, -16
	v_add_lshl_u32 v0, v21, s20, 10
	v_or_b32_e32 v24, v5, v0
	v_or_b32_e32 v0, v22, v25
	v_lshl_add_u64 v[26:27], v[0:1], 2, s[2:3]
	v_mov_b32_e32 v25, v1
	v_lshl_add_u64 v[24:25], v[24:25], 2, s[2:3]
	global_load_dword v42, v[26:27], off
	global_load_dword v43, v[24:25], off
	v_mad_u64_u32 v[60:61], s[46:47], v23, s81, v[6:7]
	v_mad_u64_u32 v[62:63], s[46:47], v21, s81, v[6:7]
	s_add_i32 s46, s29, 8
	s_add_i32 s47, s45, 8
	v_or_b32_e32 v21, s46, v3
	v_or_b32_e32 v23, s47, v2
	v_add_lshl_u32 v25, v23, s16, 10
	v_add_lshl_u32 v0, v21, s20, 10
	v_or_b32_e32 v24, v5, v0
	v_or_b32_e32 v0, v22, v25
	v_lshl_add_u64 v[26:27], v[0:1], 2, s[2:3]
	v_mov_b32_e32 v25, v1
	v_lshl_add_u64 v[24:25], v[24:25], 2, s[2:3]
	global_load_dword v44, v[26:27], off
	global_load_dword v45, v[24:25], off
	v_mad_u64_u32 v[64:65], s[46:47], v23, s81, v[6:7]
	v_mad_u64_u32 v[66:67], s[46:47], v21, s81, v[6:7]
	s_add_i32 s46, s29, 12
	s_add_i32 s47, s45, 12
	v_or_b32_e32 v21, s46, v3
	v_or_b32_e32 v23, s47, v2
	v_add_lshl_u32 v25, v23, s16, 10
	v_add_lshl_u32 v0, v21, s20, 10
	v_or_b32_e32 v24, v5, v0
	v_or_b32_e32 v0, v22, v25
	v_lshl_add_u64 v[26:27], v[0:1], 2, s[2:3]
	v_mov_b32_e32 v25, v1
	v_lshl_add_u64 v[24:25], v[24:25], 2, s[2:3]
	global_load_dword v46, v[26:27], off
	global_load_dword v47, v[24:25], off
	v_mad_u64_u32 v[68:69], s[46:47], v23, s81, v[6:7]
	v_mad_u64_u32 v[70:71], s[46:47], v21, s81, v[6:7]
	s_add_i32 s46, s29, 16
	s_add_i32 s47, s45, 16
	v_or_b32_e32 v21, s46, v3
	v_or_b32_e32 v23, s47, v2
	v_add_lshl_u32 v25, v23, s16, 10
	v_add_lshl_u32 v0, v21, s20, 10
	v_or_b32_e32 v24, v5, v0
	v_or_b32_e32 v0, v22, v25
	v_lshl_add_u64 v[26:27], v[0:1], 2, s[2:3]
	v_mov_b32_e32 v25, v1
	v_lshl_add_u64 v[24:25], v[24:25], 2, s[2:3]
	global_load_dword v48, v[26:27], off
	global_load_dword v49, v[24:25], off
	v_mad_u64_u32 v[72:73], s[46:47], v23, s81, v[6:7]
	v_mad_u64_u32 v[74:75], s[46:47], v21, s81, v[6:7]
	s_add_i32 s46, s29, 20
	s_add_i32 s47, s45, 20
	v_or_b32_e32 v21, s46, v3
	v_or_b32_e32 v23, s47, v2
	v_add_lshl_u32 v25, v23, s16, 10
	v_add_lshl_u32 v0, v21, s20, 10
	v_or_b32_e32 v24, v5, v0
	v_or_b32_e32 v0, v22, v25
	v_lshl_add_u64 v[26:27], v[0:1], 2, s[2:3]
	v_mov_b32_e32 v25, v1
	v_lshl_add_u64 v[24:25], v[24:25], 2, s[2:3]
	global_load_dword v50, v[26:27], off
	global_load_dword v51, v[24:25], off
	v_mad_u64_u32 v[76:77], s[46:47], v23, s81, v[6:7]
	v_mad_u64_u32 v[78:79], s[46:47], v21, s81, v[6:7]
	s_add_i32 s46, s29, 24
	s_add_i32 s47, s45, 24
	v_or_b32_e32 v21, s46, v3
	v_or_b32_e32 v23, s47, v2
	v_add_lshl_u32 v25, v23, s16, 10
	s_add_i32 s29, s29, 28
	s_add_i32 s45, s45, 28
	s_cmp_lg_u32 s28, 0
	v_add_lshl_u32 v0, v21, s20, 10
	v_or_b32_e32 v24, v5, v0
	v_or_b32_e32 v0, v22, v25
	v_lshl_add_u64 v[26:27], v[0:1], 2, s[2:3]
	v_mov_b32_e32 v25, v1
	v_lshl_add_u64 v[24:25], v[24:25], 2, s[2:3]
	global_load_dword v52, v[26:27], off
	global_load_dword v53, v[24:25], off
	v_mad_u64_u32 v[80:81], s[46:47], v23, s81, v[6:7]
	v_mad_u64_u32 v[82:83], s[46:47], v21, s81, v[6:7]
	v_or_b32_e32 v21, s29, v3
	v_or_b32_e32 v23, s45, v2
	v_mov_b32_e32 v27, v1
	v_add_lshl_u32 v0, v21, s20, 10
	v_add_lshl_u32 v24, v23, s16, 10
	v_or_b32_e32 v26, v5, v0
	v_or_b32_e32 v0, v22, v24
	v_lshl_add_u64 v[24:25], v[0:1], 2, s[2:3]
	v_lshl_add_u64 v[26:27], v[26:27], 2, s[2:3]
	global_load_dword v54, v[24:25], off
	global_load_dword v55, v[26:27], off
	v_mad_u64_u32 v[84:85], s[46:47], v23, s81, v[6:7]
	v_mad_u64_u32 v[86:87], s[46:47], v21, s81, v[6:7]
	s_waitcnt vmcnt(15)
	ds_write_b32 v56, v40
	s_waitcnt vmcnt(14)
	ds_write_b32 v58, v41
	s_waitcnt vmcnt(13)
	ds_write_b32 v60, v42
	s_waitcnt vmcnt(12)
	ds_write_b32 v62, v43
	s_waitcnt vmcnt(11)
	ds_write_b32 v64, v44
	s_waitcnt vmcnt(10)
	ds_write_b32 v66, v45
	s_waitcnt vmcnt(9)
	ds_write_b32 v68, v46
	s_waitcnt vmcnt(8)
	ds_write_b32 v70, v47
	s_waitcnt vmcnt(7)
	ds_write_b32 v72, v48
	s_waitcnt vmcnt(6)
	ds_write_b32 v74, v49
	s_waitcnt vmcnt(5)
	ds_write_b32 v76, v50
	s_waitcnt vmcnt(4)
	ds_write_b32 v78, v51
	s_waitcnt vmcnt(3)
	ds_write_b32 v80, v52
	s_waitcnt vmcnt(2)
	ds_write_b32 v82, v53
	s_waitcnt vmcnt(1)
	ds_write_b32 v84, v54
	s_waitcnt vmcnt(0)
	ds_write_b32 v86, v55
	s_cbranch_scc1 .LBB0_87
	s_waitcnt lgkmcnt(0)
	ds_read2_b32 v[22:23], v28 offset1:33
	s_waitcnt lgkmcnt(0)
	v_cvt_pk_bf16_f32 v22, v22, v23
	ds_read2_b32 v[24:25], v28 offset0:66 offset1:99
	s_lshl_b32 s16, s16, 1
	s_waitcnt lgkmcnt(0)
	v_cvt_pk_bf16_f32 v23, v24, v25
	ds_read2_b32 v[24:25], v28 offset0:132 offset1:165
	v_or_b32_e32 v0, s10, v7
	v_lshl_add_u64 v[26:27], v[14:15], 0, s[16:17]
	s_waitcnt lgkmcnt(0)
	v_cvt_pk_bf16_f32 v24, v24, v25
	ds_read2_b32 v[36:37], v28 offset0:198 offset1:231
	v_lshlrev_b32_e32 v0, 11, v0
	s_waitcnt lgkmcnt(0)
	v_cvt_pk_bf16_f32 v25, v36, v37
	v_lshl_add_u64 v[36:37], v[26:27], 0, v[0:1]
	global_store_dwordx4 v[36:37], v[22:25], off
	ds_read2_b32 v[22:23], v28 offset0:8 offset1:41
	v_or_b32_e32 v0, s10, v29
	s_waitcnt lgkmcnt(0)
	v_cvt_pk_bf16_f32 v22, v22, v23
	ds_read2_b32 v[24:25], v28 offset0:74 offset1:107
	s_waitcnt lgkmcnt(0)
	v_cvt_pk_bf16_f32 v23, v24, v25
	ds_read2_b32 v[24:25], v28 offset0:140 offset1:173
	s_waitcnt lgkmcnt(0)
	v_cvt_pk_bf16_f32 v24, v24, v25
	ds_read2_b32 v[36:37], v28 offset0:206 offset1:239
	v_lshlrev_b32_e32 v0, 11, v0
	s_waitcnt lgkmcnt(0)
	v_cvt_pk_bf16_f32 v25, v36, v37
	v_lshl_add_u64 v[36:37], v[26:27], 0, v[0:1]
	global_store_dwordx4 v[36:37], v[22:25], off
	ds_read2_b32 v[22:23], v28 offset0:16 offset1:49
	v_or_b32_e32 v0, s10, v30
	s_waitcnt lgkmcnt(0)
	v_cvt_pk_bf16_f32 v22, v22, v23
	ds_read2_b32 v[24:25], v28 offset0:82 offset1:115
	s_waitcnt lgkmcnt(0)
	v_cvt_pk_bf16_f32 v23, v24, v25
	ds_read2_b32 v[24:25], v28 offset0:148 offset1:181
	s_waitcnt lgkmcnt(0)
	v_cvt_pk_bf16_f32 v24, v24, v25
	ds_read2_b32 v[36:37], v28 offset0:214 offset1:247
	v_lshlrev_b32_e32 v0, 11, v0
	s_waitcnt lgkmcnt(0)
	v_cvt_pk_bf16_f32 v25, v36, v37
	v_lshl_add_u64 v[36:37], v[26:27], 0, v[0:1]
	global_store_dwordx4 v[36:37], v[22:25], off
	ds_read2_b32 v[22:23], v28 offset0:24 offset1:57
	v_or_b32_e32 v0, s10, v31
	s_waitcnt lgkmcnt(0)
	v_cvt_pk_bf16_f32 v22, v22, v23
	ds_read2_b32 v[24:25], v28 offset0:90 offset1:123
	v_lshlrev_b32_e32 v0, 11, v0
	s_waitcnt lgkmcnt(0)
	v_cvt_pk_bf16_f32 v23, v24, v25
	ds_read2_b32 v[24:25], v28 offset0:156 offset1:189
	v_lshl_add_u64 v[26:27], v[26:27], 0, v[0:1]
	s_waitcnt lgkmcnt(0)
	v_cvt_pk_bf16_f32 v24, v24, v25
	ds_read2_b32 v[36:37], v28 offset0:222 offset1:255
	s_waitcnt lgkmcnt(0)
	v_cvt_pk_bf16_f32 v25, v36, v37
	global_store_dwordx4 v[26:27], v[22:25], off
	s_waitcnt lgkmcnt(0)
	s_movk_i32 s10, 0x3bf
	s_mov_b64 s[20:21], 0x200

.LBB0_92:
	s_lshl_b32 s21, s11, 1
	s_lshl_b32 s20, s3, 1
	v_or_b32_e32 v24, s21, v0
	v_or_b32_e32 v26, s20, v5
	v_mad_i64_i32 v[24:25], s[28:29], v24, s38, v[22:23]
	v_mad_i64_i32 v[26:27], s[28:29], v26, s38, v[22:23]
	global_load_dword v40, v[24:25], off
	global_load_dword v41, v[26:27], off
	v_or_b32_e32 v21, s20, v3
	v_or_b32_e32 v36, s21, v2
	v_mad_u64_u32 v[56:57], s[28:29], v36, s81, v[6:7]
	v_mad_u64_u32 v[58:59], s[28:29], v21, s81, v[6:7]
	s_add_i32 s29, s21, 4
	s_add_i32 s28, s20, 4
	v_or_b32_e32 v21, s28, v3
	v_or_b32_e32 v36, s29, v2
	s_add_i32 s11, s11, 16
	s_add_i32 s3, s3, 16
	s_add_i32 s16, s16, -16
	v_or_b32_e32 v24, s29, v0
	v_or_b32_e32 v26, s28, v5
	v_mad_i64_i32 v[24:25], s[28:29], v24, s38, v[22:23]
	v_mad_i64_i32 v[26:27], s[28:29], v26, s38, v[22:23]
	global_load_dword v42, v[24:25], off
	global_load_dword v43, v[26:27], off
	v_mad_u64_u32 v[60:61], s[28:29], v36, s81, v[6:7]
	v_mad_u64_u32 v[62:63], s[28:29], v21, s81, v[6:7]
	s_add_i32 s29, s21, 8
	s_add_i32 s28, s20, 8
	v_or_b32_e32 v21, s28, v3
	v_or_b32_e32 v36, s29, v2
	v_or_b32_e32 v24, s29, v0
	v_or_b32_e32 v26, s28, v5
	v_mad_i64_i32 v[24:25], s[28:29], v24, s38, v[22:23]
	v_mad_i64_i32 v[26:27], s[28:29], v26, s38, v[22:23]
	global_load_dword v44, v[24:25], off
	global_load_dword v45, v[26:27], off
	v_mad_u64_u32 v[64:65], s[28:29], v36, s81, v[6:7]
	v_mad_u64_u32 v[66:67], s[28:29], v21, s81, v[6:7]
	s_add_i32 s29, s21, 12
	s_add_i32 s28, s20, 12
	v_or_b32_e32 v21, s28, v3
	v_or_b32_e32 v36, s29, v2
	v_or_b32_e32 v24, s29, v0
	v_or_b32_e32 v26, s28, v5
	v_mad_i64_i32 v[24:25], s[28:29], v24, s38, v[22:23]
	v_mad_i64_i32 v[26:27], s[28:29], v26, s38, v[22:23]
	global_load_dword v46, v[24:25], off
	global_load_dword v47, v[26:27], off
	v_mad_u64_u32 v[68:69], s[28:29], v36, s81, v[6:7]
	v_mad_u64_u32 v[70:71], s[28:29], v21, s81, v[6:7]
	s_add_i32 s29, s21, 16
	s_add_i32 s28, s20, 16
	v_or_b32_e32 v21, s28, v3
	v_or_b32_e32 v36, s29, v2
	v_or_b32_e32 v24, s29, v0
	v_or_b32_e32 v26, s28, v5
	v_mad_i64_i32 v[24:25], s[28:29], v24, s38, v[22:23]
	v_mad_i64_i32 v[26:27], s[28:29], v26, s38, v[22:23]
	global_load_dword v48, v[24:25], off
	global_load_dword v49, v[26:27], off
	v_mad_u64_u32 v[72:73], s[28:29], v36, s81, v[6:7]
	v_mad_u64_u32 v[74:75], s[28:29], v21, s81, v[6:7]
	s_add_i32 s29, s21, 20
	s_add_i32 s28, s20, 20
	v_or_b32_e32 v21, s28, v3
	v_or_b32_e32 v36, s29, v2
	v_or_b32_e32 v24, s29, v0
	v_or_b32_e32 v26, s28, v5
	v_mad_i64_i32 v[24:25], s[28:29], v24, s38, v[22:23]
	v_mad_i64_i32 v[26:27], s[28:29], v26, s38, v[22:23]
	global_load_dword v50, v[24:25], off
	global_load_dword v51, v[26:27], off
	v_mad_u64_u32 v[76:77], s[28:29], v36, s81, v[6:7]
	v_mad_u64_u32 v[78:79], s[28:29], v21, s81, v[6:7]
	s_add_i32 s29, s21, 24
	s_add_i32 s28, s20, 24
	v_or_b32_e32 v21, s28, v3
	v_or_b32_e32 v36, s29, v2
	s_add_i32 s21, s21, 28
	s_add_i32 s20, s20, 28
	s_cmp_lg_u32 s16, 0
	v_or_b32_e32 v24, s29, v0
	v_or_b32_e32 v26, s28, v5
	v_mad_i64_i32 v[24:25], s[28:29], v24, s38, v[22:23]
	v_mad_i64_i32 v[26:27], s[28:29], v26, s38, v[22:23]
	global_load_dword v52, v[24:25], off
	global_load_dword v53, v[26:27], off
	v_mad_u64_u32 v[80:81], s[28:29], v36, s81, v[6:7]
	v_mad_u64_u32 v[82:83], s[28:29], v21, s81, v[6:7]
	v_or_b32_e32 v21, s20, v3
	v_or_b32_e32 v36, s21, v2
	v_or_b32_e32 v24, s21, v0
	v_or_b32_e32 v26, s20, v5
	v_mad_i64_i32 v[24:25], s[20:21], v24, s38, v[22:23]
	v_mad_i64_i32 v[26:27], s[20:21], v26, s38, v[22:23]
	global_load_dword v54, v[24:25], off
	global_load_dword v55, v[26:27], off
	v_mad_u64_u32 v[84:85], s[20:21], v36, s81, v[6:7]
	v_mad_u64_u32 v[86:87], s[20:21], v21, s81, v[6:7]
	s_waitcnt vmcnt(15)
	ds_write_b32 v56, v40
	s_waitcnt vmcnt(14)
	ds_write_b32 v58, v41
	s_waitcnt vmcnt(13)
	ds_write_b32 v60, v42
	s_waitcnt vmcnt(12)
	ds_write_b32 v62, v43
	s_waitcnt vmcnt(11)
	ds_write_b32 v64, v44
	s_waitcnt vmcnt(10)
	ds_write_b32 v66, v45
	s_waitcnt vmcnt(9)
	ds_write_b32 v68, v46
	s_waitcnt vmcnt(8)
	ds_write_b32 v70, v47
	s_waitcnt vmcnt(7)
	ds_write_b32 v72, v48
	s_waitcnt vmcnt(6)
	ds_write_b32 v74, v49
	s_waitcnt vmcnt(5)
	ds_write_b32 v76, v50
	s_waitcnt vmcnt(4)
	ds_write_b32 v78, v51
	s_waitcnt vmcnt(3)
	ds_write_b32 v80, v52
	s_waitcnt vmcnt(2)
	ds_write_b32 v82, v53
	s_waitcnt vmcnt(1)
	ds_write_b32 v84, v54
	s_waitcnt vmcnt(0)
	ds_write_b32 v86, v55
	s_cbranch_scc1 .LBB0_92
	s_waitcnt lgkmcnt(0)
	s_ashr_i32 s11, s10, 31
	ds_read2_b32 v[24:25], v28 offset1:33
	s_add_i32 s3, s2, 0xfffffc00
	s_waitcnt lgkmcnt(0)
	v_cvt_pk_bf16_f32 v24, v24, v25
	ds_read2_b32 v[26:27], v28 offset0:66 offset1:99
	v_or_b32_e32 v0, s2, v7
	s_movk_i32 s16, 0x200
	s_cmpk_lt_u32 s3, 0x280
	v_lshl_add_u64 v[22:23], s[10:11], 1, v[8:9]
	s_waitcnt lgkmcnt(0)
	v_cvt_pk_bf16_f32 v25, v26, v27
	ds_read2_b32 v[26:27], v28 offset0:132 offset1:165
	v_cmp_gt_i32_e32 vcc, s16, v0
	s_cselect_b64 s[10:11], -1, 0
	s_waitcnt lgkmcnt(0)
	v_cvt_pk_bf16_f32 v26, v26, v27
	ds_read2_b32 v[36:37], v28 offset0:198 offset1:231
	s_or_b64 vcc, vcc, s[10:11]
	v_or_b32_e32 v5, s2, v32
	s_waitcnt lgkmcnt(0)
	v_cvt_pk_bf16_f32 v27, v36, v37
	v_cndmask_b32_e32 v36, v0, v5, vcc
	v_ashrrev_i32_e32 v37, 31, v36
	v_lshlrev_b64 v[36:37], 11, v[36:37]
	v_lshl_add_u64 v[36:37], v[22:23], 0, v[36:37]
	global_store_dwordx4 v[36:37], v[24:27], off
	ds_read2_b32 v[24:25], v28 offset0:8 offset1:41
	v_or_b32_e32 v0, s2, v29
	s_waitcnt lgkmcnt(0)
	v_cvt_pk_bf16_f32 v24, v24, v25
	ds_read2_b32 v[26:27], v28 offset0:74 offset1:107
	s_waitcnt lgkmcnt(0)
	v_cvt_pk_bf16_f32 v25, v26, v27
	ds_read2_b32 v[26:27], v28 offset0:140 offset1:173
	v_cmp_gt_i32_e32 vcc, s16, v0
	s_waitcnt lgkmcnt(0)
	v_cvt_pk_bf16_f32 v26, v26, v27
	ds_read2_b32 v[36:37], v28 offset0:206 offset1:239
	s_or_b64 vcc, vcc, s[10:11]
	v_or_b32_e32 v21, s2, v33
	s_waitcnt lgkmcnt(0)
	v_cvt_pk_bf16_f32 v27, v36, v37
	v_cndmask_b32_e32 v36, v0, v21, vcc
	v_ashrrev_i32_e32 v37, 31, v36
	v_lshlrev_b64 v[36:37], 11, v[36:37]
	v_lshl_add_u64 v[36:37], v[22:23], 0, v[36:37]
	global_store_dwordx4 v[36:37], v[24:27], off
	ds_read2_b32 v[24:25], v28 offset0:16 offset1:49
	v_or_b32_e32 v0, s2, v30
	s_waitcnt lgkmcnt(0)
	v_cvt_pk_bf16_f32 v24, v24, v25
	ds_read2_b32 v[26:27], v28 offset0:82 offset1:115
	s_waitcnt lgkmcnt(0)
	v_cvt_pk_bf16_f32 v25, v26, v27
	ds_read2_b32 v[26:27], v28 offset0:148 offset1:181
	v_cmp_gt_i32_e32 vcc, s16, v0
	s_waitcnt lgkmcnt(0)
	v_cvt_pk_bf16_f32 v26, v26, v27
	ds_read2_b32 v[36:37], v28 offset0:214 offset1:247
	s_or_b64 vcc, vcc, s[10:11]
	v_or_b32_e32 v5, 1, v5
	s_waitcnt lgkmcnt(0)
	v_cvt_pk_bf16_f32 v27, v36, v37
	v_cndmask_b32_e32 v36, v0, v5, vcc
	v_ashrrev_i32_e32 v37, 31, v36
	v_lshlrev_b64 v[36:37], 11, v[36:37]
	v_lshl_add_u64 v[36:37], v[22:23], 0, v[36:37]
	global_store_dwordx4 v[36:37], v[24:27], off
	ds_read2_b32 v[24:25], v28 offset0:24 offset1:57
	v_or_b32_e32 v0, s2, v31
	s_waitcnt lgkmcnt(0)
	v_cvt_pk_bf16_f32 v24, v24, v25
	ds_read2_b32 v[26:27], v28 offset0:90 offset1:123
	s_waitcnt lgkmcnt(0)
	v_cvt_pk_bf16_f32 v25, v26, v27
	ds_read2_b32 v[26:27], v28 offset0:156 offset1:189
	v_cmp_gt_i32_e32 vcc, s16, v0
	s_waitcnt lgkmcnt(0)
	v_cvt_pk_bf16_f32 v26, v26, v27
	ds_read2_b32 v[36:37], v28 offset0:222 offset1:255
	s_or_b64 vcc, vcc, s[10:11]
	v_or_b32_e32 v5, s2, v34
	s_waitcnt lgkmcnt(0)
	v_cvt_pk_bf16_f32 v27, v36, v37
	v_cndmask_b32_e32 v36, v0, v5, vcc
	v_ashrrev_i32_e32 v37, 31, v36
	v_lshlrev_b64 v[36:37], 11, v[36:37]
	v_lshl_add_u64 v[22:23], v[22:23], 0, v[36:37]
	global_store_dwordx4 v[22:23], v[24:27], off
	s_waitcnt lgkmcnt(0)
	s_movk_i32 s10, 0x3bf
	s_mov_b64 s[20:21], 0x200
	s_branch .LBB0_61
